# PEER u sweep: rolling prefetch, all 16 row gathers of the next item in flight while the current item is reduced
# speedup vs baseline: 1.0035x; 1.0035x over previous
; #define LAS __attribute__((address_space(3)))
; #define PB_RECS(rv, t, q) do { rv = *(const LAS recv_t*)(L + PW_REC + (t) * 512 + (g16 + NPB * (q)) * 4); } while (0)
; template <int CTRL> __device__ __forceinline__ int dppi(int v) { return __builtin_amdgcn_update_dpp(0, v, CTRL, 0xF, 0xF, true); }
; __device__ __forceinline__ int pb_u_part(const v4u (&buf)[4], const v4u& xq, int m) {
;     int d[4];
; #pragma unroll
;     for (int i = 0; i < 4; ++i) { int a = __builtin_amdgcn_sdot4((int)buf[i][0], (int)xq[0], 0, false); a = __builtin_amdgcn_sdot4((int)buf[i][1], (int)xq[1], a, false);
;         a = __builtin_amdgcn_sdot4((int)buf[i][2], (int)xq[2], a, false); d[i] = __builtin_amdgcn_sdot4((int)buf[i][3], (int)xq[3], a, false); }
;     const bool b2 = (m & 4) != 0, b1 = (m & 2) != 0;
;     const int e0 = (b2 ? d[2] : d[0]) + dppi<0x141>(b2 ? d[0] : d[2]), e1 = (b2 ? d[3] : d[1]) + dppi<0x141>(b2 ? d[1] : d[3]);
;     const int f0 = (b1 ? e1 : e0) + dppi<0x4E>(b1 ? e0 : e1);
;     return f0 + dppi<0xB1>(f0);
; __device__ __forceinline__ void peer_block(int tok0, float* X1, const unsigned short* X1B, const int* TKI, const float* TKS, __amdgpu_buffer_rsrc_t U8r, __amdgpu_buffer_rsrc_t V6, const float* USC, const float* VSC,
;                                            const float* finw, pw_ptr L, int lane) {
;     ...
;         v4u bu[NBU][4]; v4u xq;
; #pragma unroll
;         for (int q = 0; q < NBU - 1; ++q) { PB_RECS(rv, 0, q); PB_LOADU(bu[q], U8r, rv, 0); }
;         for (int it = 0; it < NSU * PT; ++it) {
;             const int c = it / PT, t = it - c * PT; const int soff = c * SLU;
;             const int itn = it + 1, cn = itn / PT, tn = itn - cn * PT;
;             int rq[4];
;             xq = *(const LAS v4u*)(L + PW_Y + t * 1024 + 128 * c + 16 * m);
; #pragma unroll
;             for (int q = 0; q < 4; ++q) {
;                 const int qa = q + NBU - 1;
;                 if (qa < 4) { PB_RECS(rv, t, qa); PB_LOADU(bu[qa % NBU], U8r, rv, soff); }
;                 else if (itn < NSU * PT) { PB_RECS(rv, tn, qa - 4); PB_LOADU(bu[qa % NBU], U8r, rv, cn * SLU); }
;                 rq[q] = pb_u_part(bu[q % NBU], xq, m);
;             }
;             LAS int* ap = (LAS int*)(L + PW_ACT + t * 512 + (g16 + 8 * (m & 1) + (m >> 1)) * 4);
;             ap[0] += (m & 1) ? rq[2] : rq[0]; ap[4] += (m & 1) ? rq[3] : rq[1];
;         }
.LBB0_691:
	s_or_b64 exec, exec, s[40:41]
	v_add_u32_e32 v44, s33, v91
	ds_read_b128 v[0:3], v44
	s_waitcnt lgkmcnt(0)
	v_mad_u32_u16 v0, v0, s48, v90
	v_mad_u32_u16 v1, v1, s48, v90
	v_mad_u32_u16 v2, v2, s48, v90
	v_mad_u32_u16 v3, v3, s48, v90
	buffer_load_dwordx4 v[12:15], v0, s[60:63], 0 offen
	buffer_load_dwordx4 v[8:11], v1, s[60:63], 0 offen
	buffer_load_dwordx4 v[4:7], v2, s[60:63], 0 offen
	s_nop 0
	buffer_load_dwordx4 v[0:3], v3, s[60:63], 0 offen
	s_mov_b32 s10, 0
	s_mov_b32 s11, 1
	s_mov_b32 s40, 0
	s_mov_b32 s41, 0
	ds_read_b128 v[136:139], v44 offset:16
	ds_read_b128 v[140:143], v44 offset:32
	ds_read_b128 v[144:147], v44 offset:48
	s_waitcnt lgkmcnt(0)
	v_mad_u32_u16 v156, v136, s48, v90
	v_mad_u32_u16 v157, v137, s48, v90
	v_mad_u32_u16 v158, v138, s48, v90
	v_mad_u32_u16 v159, v139, s48, v90
	v_mad_u32_u16 v160, v140, s48, v90
	v_mad_u32_u16 v161, v141, s48, v90
	v_mad_u32_u16 v162, v142, s48, v90
	v_mad_u32_u16 v163, v143, s48, v90
	v_mad_u32_u16 v164, v144, s48, v90
	v_mad_u32_u16 v165, v145, s48, v90
	v_mad_u32_u16 v166, v146, s48, v90
	v_mad_u32_u16 v167, v147, s48, v90
	buffer_load_dwordx4 v[16:19], v156, s[60:63], 0 offen
	buffer_load_dwordx4 v[20:23], v157, s[60:63], 0 offen
	buffer_load_dwordx4 v[24:27], v158, s[60:63], 0 offen
	buffer_load_dwordx4 v[46:49], v159, s[60:63], 0 offen
	buffer_load_dwordx4 v[50:53], v160, s[60:63], 0 offen
	buffer_load_dwordx4 v[54:57], v161, s[60:63], 0 offen
	buffer_load_dwordx4 v[58:61], v162, s[60:63], 0 offen
	buffer_load_dwordx4 v[62:65], v163, s[60:63], 0 offen
	buffer_load_dwordx4 v[66:69], v164, s[60:63], 0 offen
	buffer_load_dwordx4 v[104:107], v165, s[60:63], 0 offen
	buffer_load_dwordx4 v[108:111], v166, s[60:63], 0 offen
	buffer_load_dwordx4 v[112:115], v167, s[60:63], 0 offen
.LBB0_692:
	s_mul_hi_u32 s68, s11, 0xaaaaaaab
	s_mul_hi_u32 s71, s41, 0xaaaaaaab
	s_lshr_b32 s68, s68, 2
	s_lshr_b32 s71, s71, 2
	s_mulk_i32 s68, 0xc00
	s_mul_i32 s74, s71, 0xc00
	s_mulk_i32 s71, 0x1780
	s_add_i32 s69, s33, s10
	s_add_i32 s70, s33, s40
	v_subrev_u32_e32 v152, s68, v83
	v_subrev_u32_e32 v153, s71, v94
	v_subrev_u32_e32 v154, s74, v93
	v_add_u32_e32 v153, s69, v153
	v_add_u32_e32 v152, s70, v152
	v_add_u32_e32 v131, s70, v154
	ds_read_b128 v[28:31], v153
	ds_read_b128 v[136:139], v152
	ds_read_b128 v[140:143], v152 offset:16
	ds_read_b128 v[144:147], v152 offset:32
	ds_read_b128 v[148:151], v152 offset:48
	ds_read2_b32 v[70:71], v131 offset1:4
	s_mul_i32 s72, s11, 0x55800
	s_and_b32 s72, s72, 0x7e00000
	s_cmp_eq_u32 s11, 47
	s_cselect_b32 s73, 0x1000000, s72
	v_mov_b32_e32 v45, 0
	v_mov_b32_e32 v116, 0
	v_mov_b32_e32 v117, 0
	v_mov_b32_e32 v118, 0
	v_mov_b32_e32 v119, 0
	v_mov_b32_e32 v120, 0
	v_mov_b32_e32 v121, 0
	v_mov_b32_e32 v122, 0
	v_mov_b32_e32 v123, 0
	v_mov_b32_e32 v124, 0
	v_mov_b32_e32 v125, 0
	v_mov_b32_e32 v126, 0
	v_mov_b32_e32 v127, 0
	v_mov_b32_e32 v128, 0
	v_mov_b32_e32 v129, 0
	v_mov_b32_e32 v130, 0
	s_waitcnt lgkmcnt(5)
	s_waitcnt vmcnt(12)
	v_dot4c_i32_i8_e32 v45, v12, v28
	v_dot4c_i32_i8_e32 v116, v8, v28
	v_dot4c_i32_i8_e32 v117, v4, v28
	v_dot4c_i32_i8_e32 v118, v0, v28
	v_dot4c_i32_i8_e32 v45, v13, v29
	v_dot4c_i32_i8_e32 v116, v9, v29
	v_dot4c_i32_i8_e32 v117, v5, v29
	v_dot4c_i32_i8_e32 v118, v1, v29
	v_dot4c_i32_i8_e32 v45, v14, v30
	v_dot4c_i32_i8_e32 v116, v10, v30
	v_dot4c_i32_i8_e32 v117, v6, v30
	v_dot4c_i32_i8_e32 v118, v2, v30
	v_dot4c_i32_i8_e32 v45, v15, v31
	v_dot4c_i32_i8_e32 v116, v11, v31
	v_dot4c_i32_i8_e32 v117, v7, v31
	v_dot4c_i32_i8_e32 v118, v3, v31
	s_waitcnt lgkmcnt(4)
	v_mad_u32_u16 v152, v136, s48, v90
	v_mad_u32_u16 v153, v137, s48, v90
	v_mad_u32_u16 v154, v138, s48, v90
	v_mad_u32_u16 v155, v139, s48, v90
	buffer_load_dwordx4 v[12:15], v152, s[60:63], s72 offen
	buffer_load_dwordx4 v[8:11], v153, s[60:63], s72 offen
	buffer_load_dwordx4 v[4:7], v154, s[60:63], s72 offen
	buffer_load_dwordx4 v[0:3], v155, s[60:63], s72 offen
	s_waitcnt vmcnt(12)
	v_dot4c_i32_i8_e32 v119, v16, v28
	v_dot4c_i32_i8_e32 v120, v20, v28
	v_dot4c_i32_i8_e32 v121, v24, v28
	v_dot4c_i32_i8_e32 v122, v46, v28
	v_dot4c_i32_i8_e32 v119, v17, v29
	v_dot4c_i32_i8_e32 v120, v21, v29
	v_dot4c_i32_i8_e32 v121, v25, v29
	v_dot4c_i32_i8_e32 v122, v47, v29
	v_dot4c_i32_i8_e32 v119, v18, v30
	v_dot4c_i32_i8_e32 v120, v22, v30
	v_dot4c_i32_i8_e32 v121, v26, v30
	v_dot4c_i32_i8_e32 v122, v48, v30
	v_dot4c_i32_i8_e32 v119, v19, v31
	v_dot4c_i32_i8_e32 v120, v23, v31
	v_dot4c_i32_i8_e32 v121, v27, v31
	v_dot4c_i32_i8_e32 v122, v49, v31
	s_waitcnt lgkmcnt(3)
	v_mad_u32_u16 v152, v140, s48, v90
	v_mad_u32_u16 v153, v141, s48, v90
	v_mad_u32_u16 v154, v142, s48, v90
	v_mad_u32_u16 v155, v143, s48, v90
	buffer_load_dwordx4 v[16:19], v152, s[60:63], s73 offen
	buffer_load_dwordx4 v[20:23], v153, s[60:63], s73 offen
	buffer_load_dwordx4 v[24:27], v154, s[60:63], s73 offen
	buffer_load_dwordx4 v[46:49], v155, s[60:63], s73 offen
	s_waitcnt vmcnt(12)
	v_dot4c_i32_i8_e32 v123, v50, v28
	v_dot4c_i32_i8_e32 v124, v54, v28
	v_dot4c_i32_i8_e32 v125, v58, v28
	v_dot4c_i32_i8_e32 v126, v62, v28
	v_dot4c_i32_i8_e32 v123, v51, v29
	v_dot4c_i32_i8_e32 v124, v55, v29
	v_dot4c_i32_i8_e32 v125, v59, v29
	v_dot4c_i32_i8_e32 v126, v63, v29
	v_dot4c_i32_i8_e32 v123, v52, v30
	v_dot4c_i32_i8_e32 v124, v56, v30
	v_dot4c_i32_i8_e32 v125, v60, v30
	v_dot4c_i32_i8_e32 v126, v64, v30
	v_dot4c_i32_i8_e32 v123, v53, v31
	v_dot4c_i32_i8_e32 v124, v57, v31
	v_dot4c_i32_i8_e32 v125, v61, v31
	v_dot4c_i32_i8_e32 v126, v65, v31
	s_waitcnt lgkmcnt(2)
; #define LAS __attribute__((address_space(3)))
; #define PB_RECS(rv, t, q) do { rv = *(const LAS recv_t*)(L + PW_REC + (t) * 512 + (g16 + NPB * (q)) * 4); } while (0)
; template <int CTRL> __device__ __forceinline__ int dppi(int v) { return __builtin_amdgcn_update_dpp(0, v, CTRL, 0xF, 0xF, true); }
; __device__ __forceinline__ int pb_u_part(const v4u (&buf)[4], const v4u& xq, int m) {
;     int d[4];
; #pragma unroll
;     for (int i = 0; i < 4; ++i) { int a = __builtin_amdgcn_sdot4((int)buf[i][0], (int)xq[0], 0, false); a = __builtin_amdgcn_sdot4((int)buf[i][1], (int)xq[1], a, false);
;         a = __builtin_amdgcn_sdot4((int)buf[i][2], (int)xq[2], a, false); d[i] = __builtin_amdgcn_sdot4((int)buf[i][3], (int)xq[3], a, false); }
;     const bool b2 = (m & 4) != 0, b1 = (m & 2) != 0;
;     const int e0 = (b2 ? d[2] : d[0]) + dppi<0x141>(b2 ? d[0] : d[2]), e1 = (b2 ? d[3] : d[1]) + dppi<0x141>(b2 ? d[1] : d[3]);
;     const int f0 = (b1 ? e1 : e0) + dppi<0x4E>(b1 ? e0 : e1);
;     return f0 + dppi<0xB1>(f0);
; }
; __device__ __forceinline__ void peer_block(int tok0, float* X1, const unsigned short* X1B, const int* TKI, const float* TKS, __amdgpu_buffer_rsrc_t U8r, __amdgpu_buffer_rsrc_t V6, const float* USC, const float* VSC,
;                                            const float* finw, pw_ptr L, int lane) {
;     ...
;         for (int it = 0; it < NSU * PT; ++it) {
;             const int c = it / PT, t = it - c * PT; const int soff = c * SLU;
;             const int itn = it + 1, cn = itn / PT, tn = itn - cn * PT;
;             int rq[4];
;             xq = *(const LAS v4u*)(L + PW_Y + t * 1024 + 128 * c + 16 * m);
; #pragma unroll
;             for (int q = 0; q < 4; ++q) {
;                 const int qa = q + NBU - 1;
;                 if (qa < 4) { PB_RECS(rv, t, qa); PB_LOADU(bu[qa % NBU], U8r, rv, soff); }
;                 else if (itn < NSU * PT) { PB_RECS(rv, tn, qa - 4); PB_LOADU(bu[qa % NBU], U8r, rv, cn * SLU); }
;                 rq[q] = pb_u_part(bu[q % NBU], xq, m);
;             }
;             LAS int* ap = (LAS int*)(L + PW_ACT + t * 512 + (g16 + 8 * (m & 1) + (m >> 1)) * 4);
;             ap[0] += (m & 1) ? rq[2] : rq[0]; ap[4] += (m & 1) ? rq[3] : rq[1];
;         }
	v_mad_u32_u16 v152, v144, s48, v90
	v_mad_u32_u16 v153, v145, s48, v90
	v_mad_u32_u16 v154, v146, s48, v90
	v_mad_u32_u16 v155, v147, s48, v90
	buffer_load_dwordx4 v[50:53], v152, s[60:63], s73 offen
	buffer_load_dwordx4 v[54:57], v153, s[60:63], s73 offen
	buffer_load_dwordx4 v[58:61], v154, s[60:63], s73 offen
	buffer_load_dwordx4 v[62:65], v155, s[60:63], s73 offen
	s_waitcnt vmcnt(12)
	v_dot4c_i32_i8_e32 v127, v66, v28
	v_dot4c_i32_i8_e32 v128, v104, v28
	v_dot4c_i32_i8_e32 v129, v108, v28
	v_dot4c_i32_i8_e32 v130, v112, v28
	v_dot4c_i32_i8_e32 v127, v67, v29
	v_dot4c_i32_i8_e32 v128, v105, v29
	v_dot4c_i32_i8_e32 v129, v109, v29
	v_dot4c_i32_i8_e32 v130, v113, v29
	v_dot4c_i32_i8_e32 v127, v68, v30
	v_dot4c_i32_i8_e32 v128, v106, v30
	v_dot4c_i32_i8_e32 v129, v110, v30
	v_dot4c_i32_i8_e32 v130, v114, v30
	v_dot4c_i32_i8_e32 v127, v69, v31
	v_dot4c_i32_i8_e32 v128, v107, v31
	v_dot4c_i32_i8_e32 v129, v111, v31
	v_dot4c_i32_i8_e32 v130, v115, v31
	s_waitcnt lgkmcnt(1)
	v_mad_u32_u16 v152, v148, s48, v90
	v_mad_u32_u16 v153, v149, s48, v90
	v_mad_u32_u16 v154, v150, s48, v90
	v_mad_u32_u16 v155, v151, s48, v90
	buffer_load_dwordx4 v[66:69], v152, s[60:63], s73 offen
	buffer_load_dwordx4 v[104:107], v153, s[60:63], s73 offen
	buffer_load_dwordx4 v[108:111], v154, s[60:63], s73 offen
	buffer_load_dwordx4 v[112:115], v155, s[60:63], s73 offen
	v_cndmask_b32_e64 v156, v117, v45, s[2:3]
	v_cndmask_b32_e64 v160, v45, v117, s[2:3]
	v_cndmask_b32_e64 v157, v121, v119, s[2:3]
	v_cndmask_b32_e64 v161, v119, v121, s[2:3]
	v_cndmask_b32_e64 v158, v125, v123, s[2:3]
	v_cndmask_b32_e64 v162, v123, v125, s[2:3]
	v_cndmask_b32_e64 v159, v129, v127, s[2:3]
	v_cndmask_b32_e64 v163, v127, v129, s[2:3]
	v_cndmask_b32_e64 v168, v116, v118, s[2:3]
	v_cndmask_b32_e64 v164, v118, v116, s[2:3]
	v_cndmask_b32_e64 v169, v120, v122, s[2:3]
	v_cndmask_b32_e64 v165, v122, v120, s[2:3]
	v_cndmask_b32_e64 v170, v124, v126, s[2:3]
	v_cndmask_b32_e64 v166, v126, v124, s[2:3]
	v_cndmask_b32_e64 v171, v128, v130, s[2:3]
	v_cndmask_b32_e64 v167, v130, v128, s[2:3]
	v_add_u32_dpp v156, v160, v156 row_half_mirror row_mask:0xf bank_mask:0xf bound_ctrl:1
	v_add_u32_dpp v157, v161, v157 row_half_mirror row_mask:0xf bank_mask:0xf bound_ctrl:1
	v_add_u32_dpp v158, v162, v158 row_half_mirror row_mask:0xf bank_mask:0xf bound_ctrl:1
	v_add_u32_dpp v159, v163, v159 row_half_mirror row_mask:0xf bank_mask:0xf bound_ctrl:1
	v_add_u32_dpp v164, v168, v164 row_half_mirror row_mask:0xf bank_mask:0xf bound_ctrl:1
	v_add_u32_dpp v165, v169, v165 row_half_mirror row_mask:0xf bank_mask:0xf bound_ctrl:1
	v_add_u32_dpp v166, v170, v166 row_half_mirror row_mask:0xf bank_mask:0xf bound_ctrl:1
	v_add_u32_dpp v167, v171, v167 row_half_mirror row_mask:0xf bank_mask:0xf bound_ctrl:1
	v_cndmask_b32_e64 v160, v164, v156, s[4:5]
	v_cndmask_b32_e64 v168, v156, v164, s[4:5]
	v_cndmask_b32_e64 v161, v165, v157, s[4:5]
	v_cndmask_b32_e64 v169, v157, v165, s[4:5]
	v_cndmask_b32_e64 v162, v166, v158, s[4:5]
	v_cndmask_b32_e64 v170, v158, v166, s[4:5]
	v_cndmask_b32_e64 v163, v167, v159, s[4:5]
	v_cndmask_b32_e64 v171, v159, v167, s[4:5]
	s_add_i32 s41, s41, 1
	s_addk_i32 s40, 0x200
	v_add_u32_dpp v156, v168, v160 quad_perm:[2,3,0,1] row_mask:0xf bank_mask:0xf bound_ctrl:1
	v_add_u32_dpp v157, v169, v161 quad_perm:[2,3,0,1] row_mask:0xf bank_mask:0xf bound_ctrl:1
	v_add_u32_dpp v158, v170, v162 quad_perm:[2,3,0,1] row_mask:0xf bank_mask:0xf bound_ctrl:1
	v_add_u32_dpp v159, v171, v163 quad_perm:[2,3,0,1] row_mask:0xf bank_mask:0xf bound_ctrl:1
	s_addk_i32 s10, 0x400
	s_add_i32 s11, s11, 1
	v_add_u32_dpp v164, v156, v156 quad_perm:[1,0,3,2] row_mask:0xf bank_mask:0xf bound_ctrl:1
	v_add_u32_dpp v165, v157, v157 quad_perm:[1,0,3,2] row_mask:0xf bank_mask:0xf bound_ctrl:1
	v_add_u32_dpp v166, v158, v158 quad_perm:[1,0,3,2] row_mask:0xf bank_mask:0xf bound_ctrl:1
	v_add_u32_dpp v167, v159, v159 quad_perm:[1,0,3,2] row_mask:0xf bank_mask:0xf bound_ctrl:1
	v_cndmask_b32_e64 v160, v166, v164, s[6:7]
	v_cndmask_b32_e64 v161, v167, v165, s[6:7]
	s_waitcnt lgkmcnt(0)
	v_add_u32_e32 v160, v70, v160
	v_add_u32_e32 v161, v71, v161
	ds_write2_b32 v131, v160, v161 offset1:4
	s_cmp_eq_u32 s11, 48
	s_cbranch_scc0 .LBB0_692
	s_waitcnt vmcnt(0)
	ds_read_b128 v[16:19], v44 offset:2576
	ds_read_b128 v[46:49], v44 offset:2592
	v_add_u32_e32 v45, s33, v90
	v_mov_b32_e32 v119, 0
	v_mov_b32_e32 v116, 0
	s_waitcnt lgkmcnt(1)
	v_mad_u32_u16 v16, v16, s48, v90
	v_mad_u32_u16 v20, v17, s48, v90
	v_mad_u32_u16 v24, v18, s48, v90
	v_mad_u32_u16 v28, v19, s48, v90
	buffer_load_dwordx4 v[16:19], v16, s[60:63], s49 offen
	s_nop 0
	buffer_load_dwordx4 v[20:23], v20, s[60:63], s49 offen
	s_nop 0
	buffer_load_dwordx4 v[24:27], v24, s[60:63], s49 offen
	s_nop 0
	buffer_load_dwordx4 v[28:31], v28, s[60:63], s49 offen
	s_waitcnt lgkmcnt(0)
	v_mad_u32_u16 v46, v46, s48, v90
	buffer_load_dwordx4 v[50:53], v46, s[60:63], s49 offen
	v_mad_u32_u16 v46, v47, s48, v90
	buffer_load_dwordx4 v[54:57], v46, s[60:63], s49 offen
	v_mad_u32_u16 v46, v48, s48, v90
	buffer_load_dwordx4 v[58:61], v46, s[60:63], s49 offen
	ds_read_b128 v[62:65], v45 offset:12224
	ds_read_b128 v[66:69], v44 offset:2608
	v_mad_u32_u16 v45, v49, s48, v90
	buffer_load_dwordx4 v[46:49], v45, s[60:63], s49 offen
	v_mov_b32_e32 v117, 0
	v_mov_b32_e32 v118, 0
	s_waitcnt vmcnt(8) lgkmcnt(1)
	v_dot4c_i32_i8_e32 v119, v0, v62
	s_waitcnt lgkmcnt(0)
; __device__ __forceinline__ float row16_sum(float v) { v += dppf<0xB1>(v); v += dppf<0x4E>(v); v += dppf<0x141>(v); v += dppf<0x140>(v); return v; }
; #define LAS __attribute__((address_space(3)))
; __device__ __forceinline__ void peer_block(int tok0, float* X1, const unsigned short* X1B, const int* TKI, const float* TKS, __amdgpu_buffer_rsrc_t U8r, __amdgpu_buffer_rsrc_t V6, const float* USC, const float* VSC,
;                                            const float* finw, pw_ptr L, int lane) {
;     ...
;         for (int it = 0; it < NSU * PT; ++it) {
;             const int c = it / PT, t = it - c * PT; const int soff = c * SLU;
;             const int itn = it + 1, cn = itn / PT, tn = itn - cn * PT;
;             int rq[4];
;             xq = *(const LAS v4u*)(L + PW_Y + t * 1024 + 128 * c + 16 * m);
; #pragma unroll
;             for (int q = 0; q < 4; ++q) {
;                 const int qa = q + NBU - 1;
;                 if (qa < 4) { PB_RECS(rv, t, qa); PB_LOADU(bu[qa % NBU], U8r, rv, soff); }
;                 else if (itn < NSU * PT) { PB_RECS(rv, tn, qa - 4); PB_LOADU(bu[qa % NBU], U8r, rv, cn * SLU); }
;                 rq[q] = pb_u_part(bu[q % NBU], xq, m);
;             }
;             LAS int* ap = (LAS int*)(L + PW_ACT + t * 512 + (g16 + 8 * (m & 1) + (m >> 1)) * 4);
;             ap[0] += (m & 1) ? rq[2] : rq[0]; ap[4] += (m & 1) ? rq[3] : rq[1];
;         }
;     }
; #pragma unroll
;     for (int t = 0; t < PT; ++t) {
;         const size_t tk = (size_t)(tok0 + t);
;         const float r = *(const LAS float*)(L + PW_R + t * 8), rx = *(const LAS float*)(L + PW_R + t * 8 + 4);
;         const int i0 = *(const LAS int*)(L + PW_REC + t * 512 + lane * 4), i1 = *(const LAS int*)(L + PW_REC + t * 512 + 256 + lane * 4);
;         const size_t rk0 = ((size_t)(lane >> 4) * M + tk) * 16 + (lane & 15), rk1 = rk0 + (size_t)4 * M * 16;
;         const float s0 = TKS[rk0] * r, s1 = TKS[rk1] * r;
;         const float e0 = __expf(s0 - row16_max(s0)), e1 = __expf(s1 - row16_max(s1));
;         const float g0 = e0 / row16_sum(e0), g1 = e1 / row16_sum(e1);
;         const f32x2c sc0 = *(const f32x2c*)(USC + 2 * i0), sc1 = *(const f32x2c*)(USC + 2 * i1);
;         const float a0 = (float)*(const LAS int*)(L + PW_ACT + t * 512 + lane * 4) * rx * sc0.x, a1 = (float)*(const LAS int*)(L + PW_ACT + t * 512 + 256 + lane * 4) * rx * sc1.x;
	v_mad_u32_u16 v0, v66, s48, v90
	v_dot4c_i32_i8_e32 v116, v12, v62
	v_dot4c_i32_i8_e32 v117, v8, v62
	v_dot4c_i32_i8_e32 v118, v4, v62
	v_mad_u32_u16 v4, v67, s48, v90
	v_mad_u32_u16 v8, v68, s48, v90
	v_mad_u32_u16 v12, v69, s48, v90
	buffer_load_dwordx4 v[66:69], v0, s[60:63], s49 offen
	buffer_load_dwordx4 v[104:107], v4, s[60:63], s49 offen
	buffer_load_dwordx4 v[108:111], v8, s[60:63], s49 offen
	buffer_load_dwordx4 v[112:115], v12, s[60:63], s49 offen
	v_lshl_add_u64 v[40:41], v[78:79], 0, v[40:41]
	v_dot4c_i32_i8_e32 v117, v9, v63
	v_add_co_u32_e32 v70, vcc, s66, v40
	v_dot4c_i32_i8_e32 v117, v10, v64
	s_nop 0
	v_addc_co_u32_e32 v71, vcc, 0, v41, vcc
	v_dot4c_i32_i8_e32 v116, v13, v63
	v_dot4c_i32_i8_e32 v117, v11, v65
	global_load_dword v11, v[40:41], off
	global_load_dword v13, v[70:71], off
	v_dot4c_i32_i8_e32 v118, v5, v63
	v_dot4c_i32_i8_e32 v119, v1, v63
	v_dot4c_i32_i8_e32 v116, v14, v64
	v_dot4c_i32_i8_e32 v118, v6, v64
	v_dot4c_i32_i8_e32 v119, v2, v64
	v_mov_b32_e32 v120, 0
	v_mov_b32_e32 v121, 0
	v_mov_b32_e32 v122, 0
	v_mov_b32_e32 v123, 0
	v_dot4c_i32_i8_e32 v116, v15, v65
	v_dot4c_i32_i8_e32 v118, v7, v65
	v_dot4c_i32_i8_e32 v119, v3, v65
	v_mov_b32_e32 v124, 0
	v_mov_b32_e32 v8, 0
	v_cndmask_b32_e64 v0, v118, v116, s[2:3]
	v_cndmask_b32_e64 v1, v116, v118, s[2:3]
	v_cndmask_b32_e64 v2, v119, v117, s[2:3]
	v_cndmask_b32_e64 v3, v117, v119, s[2:3]
	v_add_u32_dpp v0, v1, v0 row_half_mirror row_mask:0xf bank_mask:0xf bound_ctrl:1
	v_mov_b32_e32 v9, 0
	v_add_u32_dpp v1, v3, v2 row_half_mirror row_mask:0xf bank_mask:0xf bound_ctrl:1
	v_cndmask_b32_e64 v2, v1, v0, s[4:5]
	v_cndmask_b32_e64 v0, v0, v1, s[4:5]
	v_mov_b32_e32 v12, 0
	v_mov_b32_e32 v14, 0
	v_add_u32_dpp v0, v0, v2 quad_perm:[2,3,0,1] row_mask:0xf bank_mask:0xf bound_ctrl:1
	ds_read2st64_b32 v[4:5], v96 offset0:12 offset1:13
	s_waitcnt vmcnt(13)
	v_dot4c_i32_i8_e32 v120, v16, v62
	s_waitcnt vmcnt(12)
	v_dot4c_i32_i8_e32 v121, v20, v62
	s_waitcnt vmcnt(11)
	v_dot4c_i32_i8_e32 v122, v24, v62
	s_waitcnt vmcnt(10)
	v_dot4c_i32_i8_e32 v123, v28, v62
	v_dot4c_i32_i8_e32 v120, v17, v63
	v_dot4c_i32_i8_e32 v121, v21, v63
	v_dot4c_i32_i8_e32 v122, v25, v63
	v_dot4c_i32_i8_e32 v123, v29, v63
	v_dot4c_i32_i8_e32 v120, v18, v64
	v_dot4c_i32_i8_e32 v121, v22, v64
	v_dot4c_i32_i8_e32 v122, v26, v64
	v_dot4c_i32_i8_e32 v123, v30, v64
	v_dot4c_i32_i8_e32 v120, v19, v65
	v_dot4c_i32_i8_e32 v121, v23, v65
	v_dot4c_i32_i8_e32 v122, v27, v65
	v_dot4c_i32_i8_e32 v123, v31, v65
	v_add_u32_dpp v6, v0, v0 quad_perm:[1,0,3,2] row_mask:0xf bank_mask:0xf bound_ctrl:1
	s_waitcnt vmcnt(9)
	v_dot4c_i32_i8_e32 v124, v50, v62
	v_cndmask_b32_e64 v0, v122, v120, s[2:3]
	v_cndmask_b32_e64 v1, v120, v122, s[2:3]
	v_cndmask_b32_e64 v2, v123, v121, s[2:3]
	v_cndmask_b32_e64 v3, v121, v123, s[2:3]
	v_add_u32_dpp v0, v1, v0 row_half_mirror row_mask:0xf bank_mask:0xf bound_ctrl:1
	v_dot4c_i32_i8_e32 v124, v51, v63
	v_add_u32_dpp v1, v3, v2 row_half_mirror row_mask:0xf bank_mask:0xf bound_ctrl:1
	v_cndmask_b32_e64 v2, v1, v0, s[4:5]
	v_cndmask_b32_e64 v0, v0, v1, s[4:5]
	v_mov_b32_e32 v1, 0
	s_waitcnt vmcnt(7)
	v_dot4c_i32_i8_e32 v1, v58, v62
	v_add_u32_dpp v0, v0, v2 quad_perm:[2,3,0,1] row_mask:0xf bank_mask:0xf bound_ctrl:1
	v_mov_b32_e32 v2, 0
	v_dot4c_i32_i8_e32 v1, v59, v63
	v_add_u32_dpp v10, v0, v0 quad_perm:[1,0,3,2] row_mask:0xf bank_mask:0xf bound_ctrl:1
	v_mov_b32_e32 v0, 0
	v_dot4c_i32_i8_e32 v0, v54, v62
	s_waitcnt vmcnt(6)
	v_dot4c_i32_i8_e32 v2, v46, v62
	v_dot4c_i32_i8_e32 v124, v52, v64
	v_dot4c_i32_i8_e32 v0, v55, v63
	v_dot4c_i32_i8_e32 v1, v60, v64
	v_dot4c_i32_i8_e32 v2, v47, v63
	v_dot4c_i32_i8_e32 v124, v53, v65
	v_dot4c_i32_i8_e32 v0, v56, v64
	v_dot4c_i32_i8_e32 v1, v61, v65
	v_dot4c_i32_i8_e32 v2, v48, v64
	v_dot4c_i32_i8_e32 v0, v57, v65
	v_dot4c_i32_i8_e32 v2, v49, v65
	v_cndmask_b32_e64 v3, v1, v124, s[2:3]
	v_cndmask_b32_e64 v1, v124, v1, s[2:3]
	s_waitcnt vmcnt(5)
	v_dot4c_i32_i8_e32 v8, v66, v62
	s_waitcnt vmcnt(4)
	v_dot4c_i32_i8_e32 v9, v104, v62
	v_add_u32_dpp v1, v1, v3 row_half_mirror row_mask:0xf bank_mask:0xf bound_ctrl:1
	v_cndmask_b32_e64 v3, v2, v0, s[2:3]
	v_cndmask_b32_e64 v0, v0, v2, s[2:3]
	s_waitcnt vmcnt(3)
	v_dot4c_i32_i8_e32 v12, v108, v62
	s_waitcnt vmcnt(2)
	v_dot4c_i32_i8_e32 v14, v112, v62
	v_add_u32_dpp v0, v0, v3 row_half_mirror row_mask:0xf bank_mask:0xf bound_ctrl:1
	v_cndmask_b32_e64 v2, v0, v1, s[4:5]
	v_cndmask_b32_e64 v0, v1, v0, s[4:5]
	v_dot4c_i32_i8_e32 v8, v67, v63
	v_dot4c_i32_i8_e32 v9, v105, v63
	v_add_u32_dpp v0, v0, v2 quad_perm:[2,3,0,1] row_mask:0xf bank_mask:0xf bound_ctrl:1
	ds_read2st64_b32 v[2:3], v96 offset1:1
	v_dot4c_i32_i8_e32 v12, v109, v63
	v_add_u32_dpp v7, v0, v0 quad_perm:[1,0,3,2] row_mask:0xf bank_mask:0xf bound_ctrl:1
	v_dot4c_i32_i8_e32 v14, v113, v63
	v_dot4c_i32_i8_e32 v8, v68, v64
	s_waitcnt lgkmcnt(0)
; __device__ __forceinline__ float row16_sum(float v) { v += dppf<0xB1>(v); v += dppf<0x4E>(v); v += dppf<0x141>(v); v += dppf<0x140>(v); return v; }
; __device__ __forceinline__ float row16_max(float v) { v = fmaxf(v, dppf<0xB1>(v)); v = fmaxf(v, dppf<0x4E>(v)); v = fmaxf(v, dppf<0x141>(v)); v = fmaxf(v, dppf<0x140>(v)); return v; }
; #define LAS __attribute__((address_space(3)))
; __device__ __forceinline__ void peer_block(int tok0, float* X1, const unsigned short* X1B, const int* TKI, const float* TKS, __amdgpu_buffer_rsrc_t U8r, __amdgpu_buffer_rsrc_t V6, const float* USC, const float* VSC,
;                                            const float* finw, pw_ptr L, int lane) {
;     ...
;     for (int t = 0; t < PT; ++t) {
;         const size_t tk = (size_t)(tok0 + t);
;         const float r = *(const LAS float*)(L + PW_R + t * 8), rx = *(const LAS float*)(L + PW_R + t * 8 + 4);
;         const int i0 = *(const LAS int*)(L + PW_REC + t * 512 + lane * 4), i1 = *(const LAS int*)(L + PW_REC + t * 512 + 256 + lane * 4);
;         const size_t rk0 = ((size_t)(lane >> 4) * M + tk) * 16 + (lane & 15), rk1 = rk0 + (size_t)4 * M * 16;
;         const float s0 = TKS[rk0] * r, s1 = TKS[rk1] * r;
;         const float e0 = __expf(s0 - row16_max(s0)), e1 = __expf(s1 - row16_max(s1));
;         const float g0 = e0 / row16_sum(e0), g1 = e1 / row16_sum(e1);
;         const f32x2c sc0 = *(const f32x2c*)(USC + 2 * i0), sc1 = *(const f32x2c*)(USC + 2 * i1);
;         const float a0 = (float)*(const LAS int*)(L + PW_ACT + t * 512 + lane * 4) * rx * sc0.x, a1 = (float)*(const LAS int*)(L + PW_ACT + t * 512 + 256 + lane * 4) * rx * sc1.x;
;         const float w0 = g0 * 0.5f * a0 * (1.0f + erff(a0 * 0.70710678118654752f)) * sc0.y, w1 = g1 * 0.5f * a1 * (1.0f + erff(a1 * 0.70710678118654752f)) * sc1.y;
	v_lshlrev_b32_e32 v0, 1, v2
	v_ashrrev_i32_e32 v1, 31, v0
	v_lshl_add_u64 v[0:1], v[0:1], 2, s[34:35]
	global_load_dwordx2 v[0:1], v[0:1], off
	v_lshlrev_b32_e32 v2, 1, v3
	v_ashrrev_i32_e32 v3, 31, v2
	v_lshl_add_u64 v[2:3], v[2:3], 2, s[34:35]
	global_load_dwordx2 v[2:3], v[2:3], off
	v_dot4c_i32_i8_e32 v9, v106, v64
	v_dot4c_i32_i8_e32 v12, v110, v64
	v_dot4c_i32_i8_e32 v14, v114, v64
	v_dot4c_i32_i8_e32 v8, v69, v65
	v_dot4c_i32_i8_e32 v9, v107, v65
	v_dot4c_i32_i8_e32 v12, v111, v65
	v_dot4c_i32_i8_e32 v14, v115, v65
	s_nop 1
	v_cndmask_b32_e64 v15, v12, v8, s[2:3]
	v_cndmask_b32_e64 v8, v8, v12, s[2:3]
	v_cndmask_b32_e64 v12, v14, v9, s[2:3]
	v_cndmask_b32_e64 v9, v9, v14, s[2:3]
	v_add_u32_dpp v8, v8, v15 row_half_mirror row_mask:0xf bank_mask:0xf bound_ctrl:1
	v_add_u32_e32 v14, 0x1400, v100
	v_add_u32_dpp v9, v9, v12 row_half_mirror row_mask:0xf bank_mask:0xf bound_ctrl:1
	v_cndmask_b32_e64 v12, v9, v8, s[4:5]
	v_cndmask_b32_e64 v8, v8, v9, s[4:5]
	v_cndmask_b32_e64 v15, v7, v6, s[6:7]
	v_mov_b32_e32 v6, s33
	v_add_u32_dpp v12, v8, v12 quad_perm:[2,3,0,1] row_mask:0xf bank_mask:0xf bound_ctrl:1
	ds_read2_b32 v[8:9], v14 offset0:128 offset1:132
	ds_read_b64 v[6:7], v6 offset:6144
	v_add_u32_dpp v12, v12, v12 quad_perm:[1,0,3,2] row_mask:0xf bank_mask:0xf bound_ctrl:1
	v_cndmask_b32_e64 v10, v12, v10, s[6:7]
	s_waitcnt lgkmcnt(1)
	v_add_u32_e32 v8, v8, v15
	v_add_u32_e32 v9, v9, v10
	ds_write2_b32 v14, v8, v9 offset0:128 offset1:132
	s_waitcnt vmcnt(3) lgkmcnt(1)
	v_mul_f32_e32 v8, v6, v11
	s_waitcnt vmcnt(2)
	v_mul_f32_e32 v9, v6, v13
	v_mov_b32_dpp v10, v8 quad_perm:[1,0,3,2] row_mask:0xf bank_mask:0xf bound_ctrl:1
	v_max_f32_e32 v10, v10, v10
	v_max_f32_e32 v8, v8, v10
	s_nop 1
	v_mov_b32_dpp v10, v8 quad_perm:[2,3,0,1] row_mask:0xf bank_mask:0xf bound_ctrl:1
	v_max_f32_e32 v10, v10, v10
	v_max_f32_e32 v8, v8, v10
	s_nop 1
	v_mov_b32_dpp v10, v8 row_half_mirror row_mask:0xf bank_mask:0xf bound_ctrl:1
	v_max_f32_e32 v10, v10, v10
	v_max_f32_e32 v8, v8, v10
	s_nop 1
	v_mov_b32_dpp v10, v8 row_mirror row_mask:0xf bank_mask:0xf bound_ctrl:1
	v_max_f32_e32 v10, v10, v10
	v_max_f32_e32 v8, v8, v10
	v_fma_f32 v8, v6, v11, -v8
	v_mul_f32_e32 v8, 0x3fb8aa3b, v8
	v_exp_f32_e32 v12, v8
	v_cvt_f32_i32_e32 v10, v4
	v_mov_b32_dpp v8, v9 quad_perm:[1,0,3,2] row_mask:0xf bank_mask:0xf bound_ctrl:1
	v_max_f32_e32 v8, v8, v8
	v_max_f32_e32 v8, v9, v8
	v_mul_f32_e32 v10, v7, v10
	s_waitcnt vmcnt(1)
	v_mul_f32_e32 v0, v0, v10
	v_mov_b32_dpp v9, v8 quad_perm:[2,3,0,1] row_mask:0xf bank_mask:0xf bound_ctrl:1
	v_max_f32_e32 v9, v9, v9
	v_max_f32_e32 v8, v8, v9
	v_mul_f32_e32 v10, 0x3f3504f3, v0
	v_cmp_nlt_f32_e64 s[10:11], |v10|, 1.0
	v_mov_b32_dpp v9, v8 row_half_mirror row_mask:0xf bank_mask:0xf bound_ctrl:1
	v_max_f32_e32 v9, v9, v9
	v_max_f32_e32 v8, v8, v9
	s_nop 1
	v_mov_b32_dpp v9, v8 row_mirror row_mask:0xf bank_mask:0xf bound_ctrl:1
	v_max_f32_e32 v9, v9, v9
	v_max_f32_e32 v8, v8, v9
	v_fma_f32 v6, v6, v13, -v8
	v_mul_f32_e32 v6, 0x3fb8aa3b, v6
	v_exp_f32_e32 v13, v6
	s_nop 0
	v_add_f32_dpp v6, v12, v12 quad_perm:[1,0,3,2] row_mask:0xf bank_mask:0xf bound_ctrl:1
	v_add_f32_dpp v9, v13, v13 quad_perm:[1,0,3,2] row_mask:0xf bank_mask:0xf bound_ctrl:1
	s_nop 0
	v_add_f32_dpp v6, v6, v6 quad_perm:[2,3,0,1] row_mask:0xf bank_mask:0xf bound_ctrl:1
	v_add_f32_dpp v4, v9, v9 quad_perm:[2,3,0,1] row_mask:0xf bank_mask:0xf bound_ctrl:1
	s_nop 0
	v_add_f32_dpp v6, v6, v6 row_half_mirror row_mask:0xf bank_mask:0xf bound_ctrl:1
	v_add_f32_dpp v4, v4, v4 row_half_mirror row_mask:0xf bank_mask:0xf bound_ctrl:1
	s_nop 0
	v_mov_b32_dpp v8, v6 row_mirror row_mask:0xf bank_mask:0xf bound_ctrl:1
	v_mov_b32_dpp v9, v4 row_mirror row_mask:0xf bank_mask:0xf bound_ctrl:1
	s_and_saveexec_b64 s[40:41], s[10:11]
	s_xor_b64 s[10:11], exec, s[40:41]
	s_cbranch_execz .LBB0_695
	v_fma_f32 v11, |v10|, s50, v102
	v_fma_f32 v11, |v10|, v11, s51
	v_fma_f32 v11, |v10|, v11, s52
	v_fma_f32 v11, |v10|, v11, s53
	v_fma_f32 v11, |v10|, v11, s54
	v_fma_f32 v11, |v10|, v11, s55
	v_fma_f32 v11, |v10|, v11, |v10|
	v_mul_f32_e32 v14, 0xbfb8aa3b, v11
	v_fma_f32 v15, v11, s56, -v14
	v_rndne_f32_e32 v16, v14
	v_fmac_f32_e32 v15, 0xb2a5705f, v11
	v_sub_f32_e32 v14, v14, v16
	v_add_f32_e32 v14, v14, v15
	v_cvt_i32_f32_e32 v15, v16
	v_exp_f32_e32 v14, v14
	v_cmp_nlt_f32_e32 vcc, s57, v11
	v_ldexp_f32 v14, v14, v15
	s_nop 0
	v_cndmask_b32_e32 v14, 0, v14, vcc
	v_cmp_ngt_f32_e32 vcc, s58, v11
	s_nop 1
	v_cndmask_b32_e32 v11, v103, v14, vcc
	v_sub_f32_e32 v11, 1.0, v11
